# mixer deferred conversions throttled (s_sleep 64 per item) to spread their HBM traffic inside the attention side's slack
# speedup vs baseline: 1.0105x; 1.0105x over previous
; __device__ void ph_prep(const P& p, float* lds) {
;     ...
;     } else if (it < NTR + NCV) {
;       int j = it - NTR;
;       if (j < 16) conv_chunk4(p.keys1, p_K1b, (size_t)j * 8192);
;       else if ((j -= 16) < 16) conv_chunk4(p.keys2, p_K2b, (size_t)j * 8192);
;       else if ((j -= 16) < 2048) conv_table_chunk4(p.pu, p_U8, (size_t)j * 8192, SU);
;       else if ((j -= 2048) < 2048) conv_table_chunk4(p.pv, p_V8, (size_t)j * 8192, SV);
;       else if ((j -= 2048) < 1024) conv_chunk4(p.p_p, p_Pb, (size_t)j * 8192);
;       else { j -= 1024; conv_chunk4(p.p_s, p_Pb + (size_t)TP * 256, (size_t)j * 8192); }
.Ldef_next:
	s_sleep 64
	s_add_u32 s50, s50, s51
	s_branch .Ldef_loop
